# attention block epilogue: 64 ds_bpermute lane^1 exchanges replaced by DPP quad_perm moves (no LDS round trips)
# baseline (speedup 1.0000x reference)
; #define SBAR() __builtin_amdgcn_sched_barrier(0)
; __device__ __forceinline__ int crow(int r, int hi) { return (r & 3) + 8 * (r >> 2) + 4 * hi; }
; #define SEAM_K0() do { VMWN(NQL); SWRITE_HK(0); SBAR(); } while (0)
; __device__ __forceinline__ void block(const BlockRef& cur, const BlockRef& nxt, int skv, char* lds, Seam& S) {
;     ...
;     SBAR(); SEAM_K0();
;     if (hi == 0) li_l[r32] = l_reg; asm volatile("s_waitcnt lgkmcnt(0)" ::: "memory");
;     float rli[16];
; #pragma unroll
;     for (int r = 0; r < 16; ++r) rli[r] = __builtin_amdgcn_rcpf(li_l[crow(r, hi)]);
;     bf16* Ow = cur.O + (size_t)(wid * QBLK) * PITCH;
; #pragma unroll
;     for (int r = 0; r < 16; ++r) { const int orow = crow(r, hi);
; #pragma unroll
;         for (int d0 = 0; d0 < 4; ++d0) { const float v = o[d0][r] * rli[r];
;             const float vn = __shfl_xor(v, 1);
;             if ((r32 & 1) == 0) *(unsigned*)(Ow + (size_t)orow * PITCH + d0 * 32 + r32) = cvtpk(v, vn); } }
.LBB0_411:
	s_waitcnt vmcnt(8)
	s_waitcnt vmcnt(9)
	ds_write_b128 v231, v[108:111] offset:32768
	s_waitcnt vmcnt(8)
	ds_write_b128 v231, v[112:115] offset:40960
	s_and_saveexec_b64 s[6:7], s[2:3]
	ds_write_b32 v209, v2
	s_or_b64 exec, exec, s[6:7]
	s_waitcnt lgkmcnt(0)
	ds_read_b128 v[80:83], v205
	v_and_b32_e32 v84, 64, v222
	v_xor_b32_e32 v2, 1, v222
	v_add_u32_e32 v84, 64, v84
	v_cmp_lt_i32_e32 vcc, v2, v84
	s_waitcnt lgkmcnt(0)
	v_rcp_f32_e32 v80, v80
	ds_read_b128 v[76:79], v205 offset:32
	ds_read_b128 v[72:75], v205 offset:64
	ds_read_b128 v[68:71], v205 offset:96
	v_cndmask_b32_e32 v2, v222, v2, vcc
	v_lshlrev_b32_e32 v2, 2, v2
	v_mul_f32_e32 v52, v52, v80
	s_lshl_b64 s[6:7], s[36:37], 12
	s_nop 3
	v_mov_b32_dpp v86, v52 quad_perm:[1,0,3,2] row_mask:0xf bank_mask:0xf
	s_add_u32 s6, s34, s6
	s_addc_u32 s7, s35, s7
	v_mov_b32_e32 v215, v3
	v_lshl_add_u64 v[84:85], s[6:7], 0, v[214:215]
	v_lshl_add_u64 v[84:85], v[84:85], 0, v[202:203]
	s_and_saveexec_b64 s[6:7], s[4:5]
	s_cbranch_execz .LBB0_415
	s_waitcnt lgkmcnt(0)
	v_cvt_pk_bf16_f32 v52, v52, v86
	global_store_dword v[84:85], v52, off
.LBB0_415:
	s_or_b64 exec, exec, s[6:7]
	v_mul_f32_e32 v36, v36, v80
	s_nop 3
	v_mov_b32_dpp v52, v36 quad_perm:[1,0,3,2] row_mask:0xf bank_mask:0xf
	s_and_saveexec_b64 s[6:7], s[4:5]
	s_cbranch_execz .LBB0_417
	s_waitcnt lgkmcnt(0)
	v_cvt_pk_bf16_f32 v36, v36, v52
	global_store_dword v[84:85], v36, off offset:64
.LBB0_417:
	s_or_b64 exec, exec, s[6:7]
	v_mul_f32_e32 v20, v20, v80
	s_nop 3
	v_mov_b32_dpp v36, v20 quad_perm:[1,0,3,2] row_mask:0xf bank_mask:0xf
	s_and_saveexec_b64 s[6:7], s[4:5]
	s_cbranch_execz .LBB0_419
	s_waitcnt lgkmcnt(0)
	v_cvt_pk_bf16_f32 v20, v20, v36
	global_store_dword v[84:85], v20, off offset:128
.LBB0_419:
	s_or_b64 exec, exec, s[6:7]
	v_mul_f32_e32 v4, v4, v80
	s_nop 3
	v_mov_b32_dpp v20, v4 quad_perm:[1,0,3,2] row_mask:0xf bank_mask:0xf
	s_and_saveexec_b64 s[6:7], s[4:5]
	s_cbranch_execz .LBB0_421
	s_waitcnt lgkmcnt(0)
	v_cvt_pk_bf16_f32 v4, v4, v20
	global_store_dword v[84:85], v4, off offset:192
.LBB0_421:
	s_or_b64 exec, exec, s[6:7]
	v_rcp_f32_e32 v4, v81
	s_waitcnt lgkmcnt(0)
	v_mul_f32_e32 v20, v53, v4
	s_nop 3
	v_mov_b32_dpp v36, v20 quad_perm:[1,0,3,2] row_mask:0xf bank_mask:0xf
	s_and_saveexec_b64 s[6:7], s[4:5]
	s_cbranch_execz .LBB0_423
	v_add_co_u32_e32 v52, vcc, 0x1000, v84
	s_waitcnt lgkmcnt(0)
	v_cvt_pk_bf16_f32 v20, v20, v36
	s_nop 0
	v_addc_co_u32_e32 v53, vcc, 0, v85, vcc
	global_store_dword v[52:53], v20, off
.LBB0_423:
	s_or_b64 exec, exec, s[6:7]
	v_mul_f32_e32 v20, v37, v4
	s_waitcnt lgkmcnt(0)
	s_nop 3
	v_mov_b32_dpp v36, v20 quad_perm:[1,0,3,2] row_mask:0xf bank_mask:0xf
	s_and_saveexec_b64 s[6:7], s[4:5]
	s_cbranch_execz .LBB0_425
	s_waitcnt lgkmcnt(0)
	v_cvt_pk_bf16_f32 v20, v20, v36
	v_add_co_u32_e32 v36, vcc, 0x1000, v84
	s_nop 1
	v_addc_co_u32_e32 v37, vcc, 0, v85, vcc
	global_store_dword v[36:37], v20, off offset:64
.LBB0_425:
	s_or_b64 exec, exec, s[6:7]
	v_mul_f32_e32 v20, v21, v4
	s_nop 3
	v_mov_b32_dpp v21, v20 quad_perm:[1,0,3,2] row_mask:0xf bank_mask:0xf
	s_and_saveexec_b64 s[6:7], s[4:5]
	s_cbranch_execz .LBB0_427
	s_waitcnt lgkmcnt(0)
	v_cvt_pk_bf16_f32 v36, v20, v21
	v_add_co_u32_e32 v20, vcc, 0x1000, v84
	s_nop 1
	v_addc_co_u32_e32 v21, vcc, 0, v85, vcc
	global_store_dword v[20:21], v36, off offset:128
.LBB0_427:
	s_or_b64 exec, exec, s[6:7]
	v_mul_f32_e32 v4, v5, v4
	s_nop 3
	v_mov_b32_dpp v5, v4 quad_perm:[1,0,3,2] row_mask:0xf bank_mask:0xf
	s_and_saveexec_b64 s[6:7], s[4:5]
	s_cbranch_execz .LBB0_429
	s_waitcnt lgkmcnt(0)
	v_cvt_pk_bf16_f32 v20, v4, v5
	v_add_co_u32_e32 v4, vcc, 0x1000, v84
	s_nop 1
	v_addc_co_u32_e32 v5, vcc, 0, v85, vcc
	global_store_dword v[4:5], v20, off offset:192
.LBB0_429:
	s_or_b64 exec, exec, s[6:7]
	v_rcp_f32_e32 v4, v82
	s_waitcnt lgkmcnt(0)
	v_mul_f32_e32 v5, v54, v4
	s_nop 3
	v_mov_b32_dpp v20, v5 quad_perm:[1,0,3,2] row_mask:0xf bank_mask:0xf
	s_and_saveexec_b64 s[6:7], s[4:5]
	s_cbranch_execz .LBB0_431
	s_waitcnt lgkmcnt(0)
	v_cvt_pk_bf16_f32 v5, v5, v20
	v_add_co_u32_e32 v20, vcc, 0x2000, v84
	s_nop 1
	v_addc_co_u32_e32 v21, vcc, 0, v85, vcc
	global_store_dword v[20:21], v5, off
.LBB0_431:
	s_or_b64 exec, exec, s[6:7]
	v_mul_f32_e32 v5, v38, v4
	s_waitcnt lgkmcnt(0)
	s_nop 3
	v_mov_b32_dpp v20, v5 quad_perm:[1,0,3,2] row_mask:0xf bank_mask:0xf
	s_and_saveexec_b64 s[6:7], s[4:5]
	s_cbranch_execz .LBB0_433
	s_waitcnt lgkmcnt(0)
	v_cvt_pk_bf16_f32 v5, v5, v20
	v_add_co_u32_e32 v20, vcc, 0x2000, v84
	s_nop 1
	v_addc_co_u32_e32 v21, vcc, 0, v85, vcc
	global_store_dword v[20:21], v5, off offset:64
.LBB0_433:
	s_or_b64 exec, exec, s[6:7]
	v_mul_f32_e32 v5, v22, v4
	s_waitcnt lgkmcnt(0)
	s_nop 3
	v_mov_b32_dpp v20, v5 quad_perm:[1,0,3,2] row_mask:0xf bank_mask:0xf
	s_and_saveexec_b64 s[6:7], s[4:5]
	s_cbranch_execz .LBB0_435
	s_waitcnt lgkmcnt(0)
	v_cvt_pk_bf16_f32 v5, v5, v20
	v_add_co_u32_e32 v20, vcc, 0x2000, v84
	s_nop 1
	v_addc_co_u32_e32 v21, vcc, 0, v85, vcc
	global_store_dword v[20:21], v5, off offset:128
.LBB0_435:
	s_or_b64 exec, exec, s[6:7]
	v_mul_f32_e32 v4, v6, v4
	s_nop 3
	v_mov_b32_dpp v5, v4 quad_perm:[1,0,3,2] row_mask:0xf bank_mask:0xf
	s_and_saveexec_b64 s[6:7], s[4:5]
	s_cbranch_execz .LBB0_437
	s_waitcnt lgkmcnt(0)
	v_cvt_pk_bf16_f32 v6, v4, v5
	v_add_co_u32_e32 v4, vcc, 0x2000, v84
	s_nop 1
	v_addc_co_u32_e32 v5, vcc, 0, v85, vcc
	global_store_dword v[4:5], v6, off offset:192
.LBB0_437:
	s_or_b64 exec, exec, s[6:7]
	v_rcp_f32_e32 v4, v83
	s_waitcnt lgkmcnt(0)
	v_mul_f32_e32 v5, v55, v4
	s_nop 3
	v_mov_b32_dpp v6, v5 quad_perm:[1,0,3,2] row_mask:0xf bank_mask:0xf
	s_and_saveexec_b64 s[6:7], s[4:5]
	s_cbranch_execz .LBB0_439
	v_add_co_u32_e32 v20, vcc, 0x3000, v84
	s_waitcnt lgkmcnt(0)
	v_cvt_pk_bf16_f32 v5, v5, v6
	s_nop 0
	v_addc_co_u32_e32 v21, vcc, 0, v85, vcc
	global_store_dword v[20:21], v5, off
; __device__ __forceinline__ int crow(int r, int hi) { return (r & 3) + 8 * (r >> 2) + 4 * hi; }
; __device__ __forceinline__ void block(const BlockRef& cur, const BlockRef& nxt, int skv, char* lds, Seam& S) {
;     ...
; #pragma unroll
;     for (int r = 0; r < 16; ++r) { const int orow = crow(r, hi);
; #pragma unroll
;         for (int d0 = 0; d0 < 4; ++d0) { const float v = o[d0][r] * rli[r];
;             const float vn = __shfl_xor(v, 1);
;             if ((r32 & 1) == 0) *(unsigned*)(Ow + (size_t)orow * PITCH + d0 * 32 + r32) = cvtpk(v, vn); } }
.LBB0_439:
	s_or_b64 exec, exec, s[6:7]
	v_mul_f32_e32 v5, v39, v4
	s_waitcnt lgkmcnt(0)
	s_nop 3
	v_mov_b32_dpp v6, v5 quad_perm:[1,0,3,2] row_mask:0xf bank_mask:0xf
	s_and_saveexec_b64 s[6:7], s[4:5]
	s_cbranch_execz .LBB0_441
	v_add_co_u32_e32 v20, vcc, 0x3000, v84
	s_waitcnt lgkmcnt(0)
	v_cvt_pk_bf16_f32 v5, v5, v6
	s_nop 0
	v_addc_co_u32_e32 v21, vcc, 0, v85, vcc
	global_store_dword v[20:21], v5, off offset:64
.LBB0_441:
	s_or_b64 exec, exec, s[6:7]
	v_mul_f32_e32 v5, v23, v4
	s_waitcnt lgkmcnt(0)
	s_nop 3
	v_mov_b32_dpp v6, v5 quad_perm:[1,0,3,2] row_mask:0xf bank_mask:0xf
	s_and_saveexec_b64 s[6:7], s[4:5]
	s_cbranch_execz .LBB0_443
	v_add_co_u32_e32 v20, vcc, 0x3000, v84
	s_waitcnt lgkmcnt(0)
	v_cvt_pk_bf16_f32 v5, v5, v6
	s_nop 0
	v_addc_co_u32_e32 v21, vcc, 0, v85, vcc
	global_store_dword v[20:21], v5, off offset:128
.LBB0_443:
	s_or_b64 exec, exec, s[6:7]
	v_mul_f32_e32 v4, v7, v4
	s_nop 3
	v_mov_b32_dpp v5, v4 quad_perm:[1,0,3,2] row_mask:0xf bank_mask:0xf
	s_and_saveexec_b64 s[6:7], s[4:5]
	s_cbranch_execz .LBB0_445
	s_waitcnt lgkmcnt(0)
	v_cvt_pk_bf16_f32 v6, v4, v5
	v_add_co_u32_e32 v4, vcc, 0x3000, v84
	s_nop 1
	v_addc_co_u32_e32 v5, vcc, 0, v85, vcc
	global_store_dword v[4:5], v6, off offset:192
.LBB0_445:
	s_or_b64 exec, exec, s[6:7]
	v_rcp_f32_e32 v4, v76
	s_waitcnt lgkmcnt(0)
	v_mul_f32_e32 v5, v56, v4
	s_nop 3
	v_mov_b32_dpp v6, v5 quad_perm:[1,0,3,2] row_mask:0xf bank_mask:0xf
	s_and_saveexec_b64 s[6:7], s[4:5]
	s_cbranch_execz .LBB0_447
	s_waitcnt lgkmcnt(0)
	v_cvt_pk_bf16_f32 v5, v5, v6
	v_add_co_u32_e32 v6, vcc, 0x8000, v84
	s_nop 1
	v_addc_co_u32_e32 v7, vcc, 0, v85, vcc
	global_store_dword v[6:7], v5, off
.LBB0_447:
	s_or_b64 exec, exec, s[6:7]
	v_mul_f32_e32 v5, v40, v4
	s_waitcnt lgkmcnt(0)
	s_nop 3
	v_mov_b32_dpp v6, v5 quad_perm:[1,0,3,2] row_mask:0xf bank_mask:0xf
	s_and_saveexec_b64 s[6:7], s[4:5]
	s_cbranch_execz .LBB0_449
	s_waitcnt lgkmcnt(0)
	v_cvt_pk_bf16_f32 v5, v5, v6
	v_add_co_u32_e32 v6, vcc, 0x8000, v84
	s_nop 1
	v_addc_co_u32_e32 v7, vcc, 0, v85, vcc
	global_store_dword v[6:7], v5, off offset:64
.LBB0_449:
	s_or_b64 exec, exec, s[6:7]
	v_mul_f32_e32 v5, v24, v4
	s_waitcnt lgkmcnt(0)
	s_nop 3
	v_mov_b32_dpp v6, v5 quad_perm:[1,0,3,2] row_mask:0xf bank_mask:0xf
	s_and_saveexec_b64 s[6:7], s[4:5]
	s_cbranch_execz .LBB0_451
	s_waitcnt lgkmcnt(0)
	v_cvt_pk_bf16_f32 v5, v5, v6
	v_add_co_u32_e32 v6, vcc, 0x8000, v84
	s_nop 1
	v_addc_co_u32_e32 v7, vcc, 0, v85, vcc
	global_store_dword v[6:7], v5, off offset:128
.LBB0_451:
	s_or_b64 exec, exec, s[6:7]
	v_mul_f32_e32 v4, v8, v4
	s_nop 3
	v_mov_b32_dpp v5, v4 quad_perm:[1,0,3,2] row_mask:0xf bank_mask:0xf
	s_and_saveexec_b64 s[6:7], s[4:5]
	s_cbranch_execz .LBB0_453
	s_waitcnt lgkmcnt(0)
	v_cvt_pk_bf16_f32 v6, v4, v5
	v_add_co_u32_e32 v4, vcc, 0x8000, v84
	s_nop 1
	v_addc_co_u32_e32 v5, vcc, 0, v85, vcc
	global_store_dword v[4:5], v6, off offset:192
.LBB0_453:
	s_or_b64 exec, exec, s[6:7]
	v_rcp_f32_e32 v4, v77
	s_waitcnt lgkmcnt(0)
	v_mul_f32_e32 v5, v57, v4
	s_nop 3
	v_mov_b32_dpp v6, v5 quad_perm:[1,0,3,2] row_mask:0xf bank_mask:0xf
	s_and_saveexec_b64 s[6:7], s[4:5]
	s_cbranch_execz .LBB0_455
	s_waitcnt lgkmcnt(0)
	v_cvt_pk_bf16_f32 v5, v5, v6
	v_add_co_u32_e32 v6, vcc, 0x9000, v84
	s_nop 1
	v_addc_co_u32_e32 v7, vcc, 0, v85, vcc
	global_store_dword v[6:7], v5, off
.LBB0_455:
	s_or_b64 exec, exec, s[6:7]
	v_mul_f32_e32 v5, v41, v4
	s_waitcnt lgkmcnt(0)
	s_nop 3
	v_mov_b32_dpp v6, v5 quad_perm:[1,0,3,2] row_mask:0xf bank_mask:0xf
	s_and_saveexec_b64 s[6:7], s[4:5]
	s_cbranch_execz .LBB0_457
	s_waitcnt lgkmcnt(0)
	v_cvt_pk_bf16_f32 v5, v5, v6
	v_add_co_u32_e32 v6, vcc, 0x9000, v84
	s_nop 1
	v_addc_co_u32_e32 v7, vcc, 0, v85, vcc
	global_store_dword v[6:7], v5, off offset:64
.LBB0_457:
	s_or_b64 exec, exec, s[6:7]
	v_mul_f32_e32 v5, v25, v4
	s_waitcnt lgkmcnt(0)
	s_nop 3
	v_mov_b32_dpp v6, v5 quad_perm:[1,0,3,2] row_mask:0xf bank_mask:0xf
	s_and_saveexec_b64 s[6:7], s[4:5]
	s_cbranch_execz .LBB0_459
	s_waitcnt lgkmcnt(0)
	v_cvt_pk_bf16_f32 v5, v5, v6
	v_add_co_u32_e32 v6, vcc, 0x9000, v84
	s_nop 1
	v_addc_co_u32_e32 v7, vcc, 0, v85, vcc
	global_store_dword v[6:7], v5, off offset:128
.LBB0_459:
	s_or_b64 exec, exec, s[6:7]
	v_mul_f32_e32 v4, v9, v4
	s_nop 3
	v_mov_b32_dpp v5, v4 quad_perm:[1,0,3,2] row_mask:0xf bank_mask:0xf
	s_and_saveexec_b64 s[6:7], s[4:5]
	s_cbranch_execz .LBB0_461
	s_waitcnt lgkmcnt(0)
	v_cvt_pk_bf16_f32 v6, v4, v5
	v_add_co_u32_e32 v4, vcc, 0x9000, v84
	s_nop 1
	v_addc_co_u32_e32 v5, vcc, 0, v85, vcc
	global_store_dword v[4:5], v6, off offset:192
.LBB0_461:
	s_or_b64 exec, exec, s[6:7]
	v_rcp_f32_e32 v4, v78
	s_waitcnt lgkmcnt(0)
	v_mul_f32_e32 v5, v58, v4
	s_nop 3
	v_mov_b32_dpp v6, v5 quad_perm:[1,0,3,2] row_mask:0xf bank_mask:0xf
	s_and_saveexec_b64 s[6:7], s[4:5]
	s_cbranch_execz .LBB0_463
	s_waitcnt lgkmcnt(0)
	v_cvt_pk_bf16_f32 v5, v5, v6
	v_add_co_u32_e32 v6, vcc, 0xa000, v84
	s_nop 1
	v_addc_co_u32_e32 v7, vcc, 0, v85, vcc
	global_store_dword v[6:7], v5, off
.LBB0_463:
	s_or_b64 exec, exec, s[6:7]
	v_mul_f32_e32 v5, v42, v4
	s_waitcnt lgkmcnt(0)
	s_nop 3
	v_mov_b32_dpp v6, v5 quad_perm:[1,0,3,2] row_mask:0xf bank_mask:0xf
	s_and_saveexec_b64 s[6:7], s[4:5]
	s_cbranch_execz .LBB0_465
	s_waitcnt lgkmcnt(0)
	v_cvt_pk_bf16_f32 v5, v5, v6
	v_add_co_u32_e32 v6, vcc, 0xa000, v84
	s_nop 1
	v_addc_co_u32_e32 v7, vcc, 0, v85, vcc
	global_store_dword v[6:7], v5, off offset:64
.LBB0_465:
	s_or_b64 exec, exec, s[6:7]
	v_mul_f32_e32 v5, v26, v4
	s_waitcnt lgkmcnt(0)
	s_nop 3
	v_mov_b32_dpp v6, v5 quad_perm:[1,0,3,2] row_mask:0xf bank_mask:0xf
	s_and_saveexec_b64 s[6:7], s[4:5]
	s_cbranch_execz .LBB0_467
	s_waitcnt lgkmcnt(0)
	v_cvt_pk_bf16_f32 v5, v5, v6
	v_add_co_u32_e32 v6, vcc, 0xa000, v84
	s_nop 1
	v_addc_co_u32_e32 v7, vcc, 0, v85, vcc
	global_store_dword v[6:7], v5, off offset:128
; __device__ __forceinline__ int crow(int r, int hi) { return (r & 3) + 8 * (r >> 2) + 4 * hi; }
; __device__ __forceinline__ void block(const BlockRef& cur, const BlockRef& nxt, int skv, char* lds, Seam& S) {
;     ...
; #pragma unroll
;     for (int r = 0; r < 16; ++r) { const int orow = crow(r, hi);
; #pragma unroll
;         for (int d0 = 0; d0 < 4; ++d0) { const float v = o[d0][r] * rli[r];
;             const float vn = __shfl_xor(v, 1);
;             if ((r32 & 1) == 0) *(unsigned*)(Ow + (size_t)orow * PITCH + d0 * 32 + r32) = cvtpk(v, vn); } }
.LBB0_467:
	s_or_b64 exec, exec, s[6:7]
	v_mul_f32_e32 v4, v10, v4
	s_nop 3
	v_mov_b32_dpp v5, v4 quad_perm:[1,0,3,2] row_mask:0xf bank_mask:0xf
	s_and_saveexec_b64 s[6:7], s[4:5]
	s_cbranch_execz .LBB0_469
	s_waitcnt lgkmcnt(0)
	v_cvt_pk_bf16_f32 v6, v4, v5
	v_add_co_u32_e32 v4, vcc, 0xa000, v84
	s_nop 1
	v_addc_co_u32_e32 v5, vcc, 0, v85, vcc
	global_store_dword v[4:5], v6, off offset:192
.LBB0_469:
	s_or_b64 exec, exec, s[6:7]
	v_rcp_f32_e32 v4, v79
	s_waitcnt lgkmcnt(0)
	v_mul_f32_e32 v5, v59, v4
	s_nop 3
	v_mov_b32_dpp v6, v5 quad_perm:[1,0,3,2] row_mask:0xf bank_mask:0xf
	s_and_saveexec_b64 s[6:7], s[4:5]
	s_cbranch_execz .LBB0_471
	s_waitcnt lgkmcnt(0)
	v_cvt_pk_bf16_f32 v5, v5, v6
	v_add_co_u32_e32 v6, vcc, 0xb000, v84
	s_nop 1
	v_addc_co_u32_e32 v7, vcc, 0, v85, vcc
	global_store_dword v[6:7], v5, off
.LBB0_471:
	s_or_b64 exec, exec, s[6:7]
	v_mul_f32_e32 v5, v43, v4
	s_waitcnt lgkmcnt(0)
	s_nop 3
	v_mov_b32_dpp v6, v5 quad_perm:[1,0,3,2] row_mask:0xf bank_mask:0xf
	s_and_saveexec_b64 s[6:7], s[4:5]
	s_cbranch_execz .LBB0_473
	s_waitcnt lgkmcnt(0)
	v_cvt_pk_bf16_f32 v5, v5, v6
	v_add_co_u32_e32 v6, vcc, 0xb000, v84
	s_nop 1
	v_addc_co_u32_e32 v7, vcc, 0, v85, vcc
	global_store_dword v[6:7], v5, off offset:64
.LBB0_473:
	s_or_b64 exec, exec, s[6:7]
	v_mul_f32_e32 v5, v27, v4
	s_waitcnt lgkmcnt(0)
	s_nop 3
	v_mov_b32_dpp v6, v5 quad_perm:[1,0,3,2] row_mask:0xf bank_mask:0xf
	s_and_saveexec_b64 s[6:7], s[4:5]
	s_cbranch_execz .LBB0_475
	s_waitcnt lgkmcnt(0)
	v_cvt_pk_bf16_f32 v5, v5, v6
	v_add_co_u32_e32 v6, vcc, 0xb000, v84
	s_nop 1
	v_addc_co_u32_e32 v7, vcc, 0, v85, vcc
	global_store_dword v[6:7], v5, off offset:128
.LBB0_475:
	s_or_b64 exec, exec, s[6:7]
	v_mul_f32_e32 v4, v11, v4
	s_nop 3
	v_mov_b32_dpp v5, v4 quad_perm:[1,0,3,2] row_mask:0xf bank_mask:0xf
	s_and_saveexec_b64 s[6:7], s[4:5]
	s_cbranch_execz .LBB0_477
	s_waitcnt lgkmcnt(0)
	v_cvt_pk_bf16_f32 v6, v4, v5
	v_add_co_u32_e32 v4, vcc, 0xb000, v84
	s_nop 1
	v_addc_co_u32_e32 v5, vcc, 0, v85, vcc
	global_store_dword v[4:5], v6, off offset:192
.LBB0_477:
	s_or_b64 exec, exec, s[6:7]
	v_rcp_f32_e32 v4, v72
	s_waitcnt lgkmcnt(0)
	v_mul_f32_e32 v5, v60, v4
	s_nop 3
	v_mov_b32_dpp v6, v5 quad_perm:[1,0,3,2] row_mask:0xf bank_mask:0xf
	s_and_saveexec_b64 s[6:7], s[4:5]
	s_cbranch_execz .LBB0_479
	s_waitcnt lgkmcnt(0)
	v_cvt_pk_bf16_f32 v5, v5, v6
	v_add_co_u32_e32 v6, vcc, 0x10000, v84
	s_nop 1
	v_addc_co_u32_e32 v7, vcc, 0, v85, vcc
	global_store_dword v[6:7], v5, off
.LBB0_479:
	s_or_b64 exec, exec, s[6:7]
	v_mul_f32_e32 v5, v44, v4
	s_waitcnt lgkmcnt(0)
	s_nop 3
	v_mov_b32_dpp v6, v5 quad_perm:[1,0,3,2] row_mask:0xf bank_mask:0xf
	s_and_saveexec_b64 s[6:7], s[4:5]
	s_cbranch_execz .LBB0_481
	s_waitcnt lgkmcnt(0)
	v_cvt_pk_bf16_f32 v5, v5, v6
	v_add_co_u32_e32 v6, vcc, 0x10000, v84
	s_nop 1
	v_addc_co_u32_e32 v7, vcc, 0, v85, vcc
	global_store_dword v[6:7], v5, off offset:64
.LBB0_481:
	s_or_b64 exec, exec, s[6:7]
	v_mul_f32_e32 v5, v28, v4
	s_waitcnt lgkmcnt(0)
	s_nop 3
	v_mov_b32_dpp v6, v5 quad_perm:[1,0,3,2] row_mask:0xf bank_mask:0xf
	s_and_saveexec_b64 s[6:7], s[4:5]
	s_cbranch_execz .LBB0_483
	s_waitcnt lgkmcnt(0)
	v_cvt_pk_bf16_f32 v5, v5, v6
	v_add_co_u32_e32 v6, vcc, 0x10000, v84
	s_nop 1
	v_addc_co_u32_e32 v7, vcc, 0, v85, vcc
	global_store_dword v[6:7], v5, off offset:128
.LBB0_483:
	s_or_b64 exec, exec, s[6:7]
	v_mul_f32_e32 v4, v12, v4
	s_nop 3
	v_mov_b32_dpp v5, v4 quad_perm:[1,0,3,2] row_mask:0xf bank_mask:0xf
	s_and_saveexec_b64 s[6:7], s[4:5]
	s_cbranch_execz .LBB0_485
	s_waitcnt lgkmcnt(0)
	v_cvt_pk_bf16_f32 v6, v4, v5
	v_add_co_u32_e32 v4, vcc, 0x10000, v84
	s_nop 1
	v_addc_co_u32_e32 v5, vcc, 0, v85, vcc
	global_store_dword v[4:5], v6, off offset:192
.LBB0_485:
	s_or_b64 exec, exec, s[6:7]
	v_rcp_f32_e32 v4, v73
	s_waitcnt lgkmcnt(0)
	v_mul_f32_e32 v5, v61, v4
	s_nop 3
	v_mov_b32_dpp v6, v5 quad_perm:[1,0,3,2] row_mask:0xf bank_mask:0xf
	s_and_saveexec_b64 s[6:7], s[4:5]
	s_cbranch_execz .LBB0_487
	s_waitcnt lgkmcnt(0)
	v_cvt_pk_bf16_f32 v5, v5, v6
	v_add_co_u32_e32 v6, vcc, 0x11000, v84
	s_nop 1
	v_addc_co_u32_e32 v7, vcc, 0, v85, vcc
	global_store_dword v[6:7], v5, off
.LBB0_487:
	s_or_b64 exec, exec, s[6:7]
	v_mul_f32_e32 v5, v45, v4
	s_waitcnt lgkmcnt(0)
	s_nop 3
	v_mov_b32_dpp v6, v5 quad_perm:[1,0,3,2] row_mask:0xf bank_mask:0xf
	s_and_saveexec_b64 s[6:7], s[4:5]
	s_cbranch_execz .LBB0_489
	s_waitcnt lgkmcnt(0)
	v_cvt_pk_bf16_f32 v5, v5, v6
	v_add_co_u32_e32 v6, vcc, 0x11000, v84
	s_nop 1
	v_addc_co_u32_e32 v7, vcc, 0, v85, vcc
	global_store_dword v[6:7], v5, off offset:64
.LBB0_489:
	s_or_b64 exec, exec, s[6:7]
	v_mul_f32_e32 v5, v29, v4
	s_waitcnt lgkmcnt(0)
	s_nop 3
	v_mov_b32_dpp v6, v5 quad_perm:[1,0,3,2] row_mask:0xf bank_mask:0xf
	s_and_saveexec_b64 s[6:7], s[4:5]
	s_cbranch_execz .LBB0_491
	s_waitcnt lgkmcnt(0)
	v_cvt_pk_bf16_f32 v5, v5, v6
	v_add_co_u32_e32 v6, vcc, 0x11000, v84
	s_nop 1
	v_addc_co_u32_e32 v7, vcc, 0, v85, vcc
	global_store_dword v[6:7], v5, off offset:128
.LBB0_491:
	s_or_b64 exec, exec, s[6:7]
	v_mul_f32_e32 v4, v13, v4
	s_nop 3
	v_mov_b32_dpp v5, v4 quad_perm:[1,0,3,2] row_mask:0xf bank_mask:0xf
	s_and_saveexec_b64 s[6:7], s[4:5]
	s_cbranch_execz .LBB0_493
	s_waitcnt lgkmcnt(0)
	v_cvt_pk_bf16_f32 v6, v4, v5
	v_add_co_u32_e32 v4, vcc, 0x11000, v84
	s_nop 1
	v_addc_co_u32_e32 v5, vcc, 0, v85, vcc
	global_store_dword v[4:5], v6, off offset:192
.LBB0_493:
	s_or_b64 exec, exec, s[6:7]
	v_rcp_f32_e32 v4, v74
	s_waitcnt lgkmcnt(0)
	v_mul_f32_e32 v5, v62, v4
	s_nop 3
	v_mov_b32_dpp v6, v5 quad_perm:[1,0,3,2] row_mask:0xf bank_mask:0xf
	s_and_saveexec_b64 s[6:7], s[4:5]
	s_cbranch_execz .LBB0_495
	s_waitcnt lgkmcnt(0)
	v_cvt_pk_bf16_f32 v5, v5, v6
	v_add_co_u32_e32 v6, vcc, 0x12000, v84
	s_nop 1
	v_addc_co_u32_e32 v7, vcc, 0, v85, vcc
	global_store_dword v[6:7], v5, off
; __device__ __forceinline__ int crow(int r, int hi) { return (r & 3) + 8 * (r >> 2) + 4 * hi; }
; __device__ __forceinline__ void block(const BlockRef& cur, const BlockRef& nxt, int skv, char* lds, Seam& S) {
;     ...
; #pragma unroll
;     for (int r = 0; r < 16; ++r) { const int orow = crow(r, hi);
; #pragma unroll
;         for (int d0 = 0; d0 < 4; ++d0) { const float v = o[d0][r] * rli[r];
;             const float vn = __shfl_xor(v, 1);
;             if ((r32 & 1) == 0) *(unsigned*)(Ow + (size_t)orow * PITCH + d0 * 32 + r32) = cvtpk(v, vn); } }
.LBB0_495:
	s_or_b64 exec, exec, s[6:7]
	v_mul_f32_e32 v5, v46, v4
	s_waitcnt lgkmcnt(0)
	s_nop 3
	v_mov_b32_dpp v6, v5 quad_perm:[1,0,3,2] row_mask:0xf bank_mask:0xf
	s_and_saveexec_b64 s[6:7], s[4:5]
	s_cbranch_execz .LBB0_497
	s_waitcnt lgkmcnt(0)
	v_cvt_pk_bf16_f32 v5, v5, v6
	v_add_co_u32_e32 v6, vcc, 0x12000, v84
	s_nop 1
	v_addc_co_u32_e32 v7, vcc, 0, v85, vcc
	global_store_dword v[6:7], v5, off offset:64
.LBB0_497:
	s_or_b64 exec, exec, s[6:7]
	v_mul_f32_e32 v5, v30, v4
	s_waitcnt lgkmcnt(0)
	s_nop 3
	v_mov_b32_dpp v6, v5 quad_perm:[1,0,3,2] row_mask:0xf bank_mask:0xf
	s_and_saveexec_b64 s[6:7], s[4:5]
	s_cbranch_execz .LBB0_499
	s_waitcnt lgkmcnt(0)
	v_cvt_pk_bf16_f32 v5, v5, v6
	v_add_co_u32_e32 v6, vcc, 0x12000, v84
	s_nop 1
	v_addc_co_u32_e32 v7, vcc, 0, v85, vcc
	global_store_dword v[6:7], v5, off offset:128
.LBB0_499:
	s_or_b64 exec, exec, s[6:7]
	v_mul_f32_e32 v4, v14, v4
	s_nop 3
	v_mov_b32_dpp v5, v4 quad_perm:[1,0,3,2] row_mask:0xf bank_mask:0xf
	s_and_saveexec_b64 s[6:7], s[4:5]
	s_cbranch_execz .LBB0_501
	s_waitcnt lgkmcnt(0)
	v_cvt_pk_bf16_f32 v6, v4, v5
	v_add_co_u32_e32 v4, vcc, 0x12000, v84
	s_nop 1
	v_addc_co_u32_e32 v5, vcc, 0, v85, vcc
	global_store_dword v[4:5], v6, off offset:192
.LBB0_501:
	s_or_b64 exec, exec, s[6:7]
	v_rcp_f32_e32 v4, v75
	s_waitcnt lgkmcnt(0)
	v_mul_f32_e32 v5, v63, v4
	s_nop 3
	v_mov_b32_dpp v6, v5 quad_perm:[1,0,3,2] row_mask:0xf bank_mask:0xf
	s_and_saveexec_b64 s[6:7], s[4:5]
	s_cbranch_execz .LBB0_503
	s_waitcnt lgkmcnt(0)
	v_cvt_pk_bf16_f32 v5, v5, v6
	v_add_co_u32_e32 v6, vcc, 0x13000, v84
	s_nop 1
	v_addc_co_u32_e32 v7, vcc, 0, v85, vcc
	global_store_dword v[6:7], v5, off
.LBB0_503:
	s_or_b64 exec, exec, s[6:7]
	v_mul_f32_e32 v5, v47, v4
	s_waitcnt lgkmcnt(0)
	s_nop 3
	v_mov_b32_dpp v6, v5 quad_perm:[1,0,3,2] row_mask:0xf bank_mask:0xf
	s_and_saveexec_b64 s[6:7], s[4:5]
	s_cbranch_execz .LBB0_505
	s_waitcnt lgkmcnt(0)
	v_cvt_pk_bf16_f32 v5, v5, v6
	v_add_co_u32_e32 v6, vcc, 0x13000, v84
	s_nop 1
	v_addc_co_u32_e32 v7, vcc, 0, v85, vcc
	global_store_dword v[6:7], v5, off offset:64
.LBB0_505:
	s_or_b64 exec, exec, s[6:7]
	v_mul_f32_e32 v5, v31, v4
	s_waitcnt lgkmcnt(0)
	s_nop 3
	v_mov_b32_dpp v6, v5 quad_perm:[1,0,3,2] row_mask:0xf bank_mask:0xf
	s_and_saveexec_b64 s[6:7], s[4:5]
	s_cbranch_execz .LBB0_507
	s_waitcnt lgkmcnt(0)
	v_cvt_pk_bf16_f32 v5, v5, v6
	v_add_co_u32_e32 v6, vcc, 0x13000, v84
	s_nop 1
	v_addc_co_u32_e32 v7, vcc, 0, v85, vcc
	global_store_dword v[6:7], v5, off offset:128
.LBB0_507:
	s_or_b64 exec, exec, s[6:7]
	v_mul_f32_e32 v4, v15, v4
	s_nop 3
	v_mov_b32_dpp v5, v4 quad_perm:[1,0,3,2] row_mask:0xf bank_mask:0xf
	s_and_saveexec_b64 s[6:7], s[4:5]
	s_cbranch_execz .LBB0_509
	s_waitcnt lgkmcnt(0)
	v_cvt_pk_bf16_f32 v6, v4, v5
	v_add_co_u32_e32 v4, vcc, 0x13000, v84
	s_nop 1
	v_addc_co_u32_e32 v5, vcc, 0, v85, vcc
	global_store_dword v[4:5], v6, off offset:192
.LBB0_509:
	s_or_b64 exec, exec, s[6:7]
	v_rcp_f32_e32 v4, v68
	s_waitcnt lgkmcnt(0)
	v_mul_f32_e32 v5, v64, v4
	s_nop 3
	v_mov_b32_dpp v6, v5 quad_perm:[1,0,3,2] row_mask:0xf bank_mask:0xf
	s_and_saveexec_b64 s[6:7], s[4:5]
	s_cbranch_execz .LBB0_511
	s_waitcnt lgkmcnt(0)
	v_cvt_pk_bf16_f32 v5, v5, v6
	v_add_co_u32_e32 v6, vcc, 0x18000, v84
	s_nop 1
	v_addc_co_u32_e32 v7, vcc, 0, v85, vcc
	global_store_dword v[6:7], v5, off
.LBB0_511:
	s_or_b64 exec, exec, s[6:7]
	v_mul_f32_e32 v5, v48, v4
	s_waitcnt lgkmcnt(0)
	s_nop 3
	v_mov_b32_dpp v6, v5 quad_perm:[1,0,3,2] row_mask:0xf bank_mask:0xf
	s_and_saveexec_b64 s[6:7], s[4:5]
	s_cbranch_execz .LBB0_513
	s_waitcnt lgkmcnt(0)
	v_cvt_pk_bf16_f32 v5, v5, v6
	v_add_co_u32_e32 v6, vcc, 0x18000, v84
	s_nop 1
	v_addc_co_u32_e32 v7, vcc, 0, v85, vcc
	global_store_dword v[6:7], v5, off offset:64
.LBB0_513:
	s_or_b64 exec, exec, s[6:7]
	v_mul_f32_e32 v5, v32, v4
	s_waitcnt lgkmcnt(0)
	s_nop 3
	v_mov_b32_dpp v6, v5 quad_perm:[1,0,3,2] row_mask:0xf bank_mask:0xf
	s_and_saveexec_b64 s[6:7], s[4:5]
	s_cbranch_execz .LBB0_515
	s_waitcnt lgkmcnt(0)
	v_cvt_pk_bf16_f32 v5, v5, v6
	v_add_co_u32_e32 v6, vcc, 0x18000, v84
	s_nop 1
	v_addc_co_u32_e32 v7, vcc, 0, v85, vcc
	global_store_dword v[6:7], v5, off offset:128
.LBB0_515:
	s_or_b64 exec, exec, s[6:7]
	v_mul_f32_e32 v4, v16, v4
	s_nop 3
	v_mov_b32_dpp v5, v4 quad_perm:[1,0,3,2] row_mask:0xf bank_mask:0xf
	s_and_saveexec_b64 s[6:7], s[4:5]
	s_cbranch_execz .LBB0_517
	s_waitcnt lgkmcnt(0)
	v_cvt_pk_bf16_f32 v6, v4, v5
	v_add_co_u32_e32 v4, vcc, 0x18000, v84
	s_nop 1
	v_addc_co_u32_e32 v5, vcc, 0, v85, vcc
	global_store_dword v[4:5], v6, off offset:192
; __device__ __forceinline__ int crow(int r, int hi) { return (r & 3) + 8 * (r >> 2) + 4 * hi; }
; __device__ __forceinline__ void block(const BlockRef& cur, const BlockRef& nxt, int skv, char* lds, Seam& S) {
;     ...
; #pragma unroll
;     for (int r = 0; r < 16; ++r) { const int orow = crow(r, hi);
; #pragma unroll
;         for (int d0 = 0; d0 < 4; ++d0) { const float v = o[d0][r] * rli[r];
;             const float vn = __shfl_xor(v, 1);
;             if ((r32 & 1) == 0) *(unsigned*)(Ow + (size_t)orow * PITCH + d0 * 32 + r32) = cvtpk(v, vn); } }
.LBB0_517:
	s_or_b64 exec, exec, s[6:7]
	v_rcp_f32_e32 v4, v69
	s_waitcnt lgkmcnt(0)
	v_mul_f32_e32 v5, v65, v4
	s_nop 3
	v_mov_b32_dpp v6, v5 quad_perm:[1,0,3,2] row_mask:0xf bank_mask:0xf
	s_and_saveexec_b64 s[6:7], s[4:5]
	s_cbranch_execz .LBB0_519
	s_waitcnt lgkmcnt(0)
	v_cvt_pk_bf16_f32 v5, v5, v6
	v_add_co_u32_e32 v6, vcc, 0x19000, v84
	s_nop 1
	v_addc_co_u32_e32 v7, vcc, 0, v85, vcc
	global_store_dword v[6:7], v5, off
.LBB0_519:
	s_or_b64 exec, exec, s[6:7]
	v_mul_f32_e32 v5, v49, v4
	s_waitcnt lgkmcnt(0)
	s_nop 3
	v_mov_b32_dpp v6, v5 quad_perm:[1,0,3,2] row_mask:0xf bank_mask:0xf
	s_and_saveexec_b64 s[6:7], s[4:5]
	s_cbranch_execz .LBB0_521
	s_waitcnt lgkmcnt(0)
	v_cvt_pk_bf16_f32 v5, v5, v6
	v_add_co_u32_e32 v6, vcc, 0x19000, v84
	s_nop 1
	v_addc_co_u32_e32 v7, vcc, 0, v85, vcc
	global_store_dword v[6:7], v5, off offset:64
.LBB0_521:
	s_or_b64 exec, exec, s[6:7]
	v_mul_f32_e32 v5, v33, v4
	s_waitcnt lgkmcnt(0)
	s_nop 3
	v_mov_b32_dpp v6, v5 quad_perm:[1,0,3,2] row_mask:0xf bank_mask:0xf
	s_and_saveexec_b64 s[6:7], s[4:5]
	s_cbranch_execz .LBB0_523
	s_waitcnt lgkmcnt(0)
	v_cvt_pk_bf16_f32 v5, v5, v6
	v_add_co_u32_e32 v6, vcc, 0x19000, v84
	s_nop 1
	v_addc_co_u32_e32 v7, vcc, 0, v85, vcc
	global_store_dword v[6:7], v5, off offset:128
.LBB0_523:
	s_or_b64 exec, exec, s[6:7]
	v_mul_f32_e32 v4, v17, v4
	s_nop 3
	v_mov_b32_dpp v5, v4 quad_perm:[1,0,3,2] row_mask:0xf bank_mask:0xf
	s_and_saveexec_b64 s[6:7], s[4:5]
	s_cbranch_execz .LBB0_525
	s_waitcnt lgkmcnt(0)
	v_cvt_pk_bf16_f32 v6, v4, v5
	v_add_co_u32_e32 v4, vcc, 0x19000, v84
	s_nop 1
	v_addc_co_u32_e32 v5, vcc, 0, v85, vcc
	global_store_dword v[4:5], v6, off offset:192
.LBB0_525:
	s_or_b64 exec, exec, s[6:7]
	v_rcp_f32_e32 v4, v70
	s_waitcnt lgkmcnt(0)
	v_mul_f32_e32 v5, v66, v4
	s_nop 3
	v_mov_b32_dpp v6, v5 quad_perm:[1,0,3,2] row_mask:0xf bank_mask:0xf
	s_and_saveexec_b64 s[6:7], s[4:5]
	s_cbranch_execz .LBB0_527
	s_waitcnt lgkmcnt(0)
	v_cvt_pk_bf16_f32 v5, v5, v6
	v_add_co_u32_e32 v6, vcc, 0x1a000, v84
	s_nop 1
	v_addc_co_u32_e32 v7, vcc, 0, v85, vcc
	global_store_dword v[6:7], v5, off
.LBB0_527:
	s_or_b64 exec, exec, s[6:7]
	v_mul_f32_e32 v5, v50, v4
	s_waitcnt lgkmcnt(0)
	s_nop 3
	v_mov_b32_dpp v6, v5 quad_perm:[1,0,3,2] row_mask:0xf bank_mask:0xf
	s_and_saveexec_b64 s[6:7], s[4:5]
	s_cbranch_execz .LBB0_529
	s_waitcnt lgkmcnt(0)
	v_cvt_pk_bf16_f32 v5, v5, v6
	v_add_co_u32_e32 v6, vcc, 0x1a000, v84
	s_nop 1
	v_addc_co_u32_e32 v7, vcc, 0, v85, vcc
	global_store_dword v[6:7], v5, off offset:64
.LBB0_529:
	s_or_b64 exec, exec, s[6:7]
	v_mul_f32_e32 v5, v34, v4
	s_waitcnt lgkmcnt(0)
	s_nop 3
	v_mov_b32_dpp v6, v5 quad_perm:[1,0,3,2] row_mask:0xf bank_mask:0xf
	s_and_saveexec_b64 s[6:7], s[4:5]
	s_cbranch_execz .LBB0_531
	s_waitcnt lgkmcnt(0)
	v_cvt_pk_bf16_f32 v5, v5, v6
	v_add_co_u32_e32 v6, vcc, 0x1a000, v84
	s_nop 1
	v_addc_co_u32_e32 v7, vcc, 0, v85, vcc
	global_store_dword v[6:7], v5, off offset:128
.LBB0_531:
	s_or_b64 exec, exec, s[6:7]
	v_mul_f32_e32 v4, v18, v4
	s_nop 3
	v_mov_b32_dpp v5, v4 quad_perm:[1,0,3,2] row_mask:0xf bank_mask:0xf
	s_and_saveexec_b64 s[6:7], s[4:5]
	s_cbranch_execz .LBB0_533
	s_waitcnt lgkmcnt(0)
	v_cvt_pk_bf16_f32 v6, v4, v5
	v_add_co_u32_e32 v4, vcc, 0x1a000, v84
	s_nop 1
	v_addc_co_u32_e32 v5, vcc, 0, v85, vcc
	global_store_dword v[4:5], v6, off offset:192
.LBB0_533:
	s_or_b64 exec, exec, s[6:7]
	v_rcp_f32_e32 v4, v71
	s_waitcnt lgkmcnt(0)
	v_mul_f32_e32 v5, v67, v4
	s_nop 3
	v_mov_b32_dpp v6, v5 quad_perm:[1,0,3,2] row_mask:0xf bank_mask:0xf
	s_and_saveexec_b64 s[6:7], s[4:5]
	s_cbranch_execz .LBB0_535
	s_waitcnt lgkmcnt(0)
	v_cvt_pk_bf16_f32 v5, v5, v6
	v_add_co_u32_e32 v6, vcc, 0x1b000, v84
	s_nop 1
	v_addc_co_u32_e32 v7, vcc, 0, v85, vcc
	global_store_dword v[6:7], v5, off
.LBB0_535:
	s_or_b64 exec, exec, s[6:7]
	v_mul_f32_e32 v5, v51, v4
	s_waitcnt lgkmcnt(0)
	s_nop 3
	v_mov_b32_dpp v6, v5 quad_perm:[1,0,3,2] row_mask:0xf bank_mask:0xf
	s_and_saveexec_b64 s[6:7], s[4:5]
	s_cbranch_execz .LBB0_537
	s_waitcnt lgkmcnt(0)
	v_cvt_pk_bf16_f32 v5, v5, v6
	v_add_co_u32_e32 v6, vcc, 0x1b000, v84
	s_nop 1
	v_addc_co_u32_e32 v7, vcc, 0, v85, vcc
	global_store_dword v[6:7], v5, off offset:64
.LBB0_537:
	s_or_b64 exec, exec, s[6:7]
	v_mul_f32_e32 v5, v35, v4
	s_waitcnt lgkmcnt(0)
	s_nop 3
	v_mov_b32_dpp v6, v5 quad_perm:[1,0,3,2] row_mask:0xf bank_mask:0xf
	s_and_saveexec_b64 s[6:7], s[4:5]
	s_cbranch_execz .LBB0_539
	s_waitcnt lgkmcnt(0)
	v_cvt_pk_bf16_f32 v5, v5, v6
	v_add_co_u32_e32 v6, vcc, 0x1b000, v84
	s_nop 1
	v_addc_co_u32_e32 v7, vcc, 0, v85, vcc
	global_store_dword v[6:7], v5, off offset:128
.LBB0_539:
	s_or_b64 exec, exec, s[6:7]
	v_mul_f32_e32 v4, v19, v4
	s_nop 3
	v_mov_b32_dpp v2, v4 quad_perm:[1,0,3,2] row_mask:0xf bank_mask:0xf
	s_and_saveexec_b64 s[6:7], s[4:5]
	s_cbranch_execz .LBB0_541
	s_waitcnt lgkmcnt(0)
	v_cvt_pk_bf16_f32 v2, v4, v2
	v_add_co_u32_e32 v4, vcc, 0x1b000, v84
	s_nop 1
	v_addc_co_u32_e32 v5, vcc, 0, v85, vcc
	global_store_dword v[4:5], v2, off offset:192
